# combo13: combo11 + P0 p->bf16 conversion loop processes 4 items per lane per trip with counted vmcnt (8 loads in flight)
# baseline (speedup 1.0000x reference)
; __device__ __forceinline__ unsigned pk2(float lo, float hi) { f32x2_t v = {lo, hi}; bf16x2_t b = __builtin_convertvector(v, bf16x2_t); return __builtin_bit_cast(unsigned, b); }
; #define AIN(i) (kargs()->in[i])
; #define K_TID ((wave_s << 6) | lane_fresh())
; __global__ void __launch_bounds__(512, 2) fwd_megakernel(Args a) {
;     ...
;         const size_t n8 = (size_t)2 * T * PLED / 8; const float* pp_ = AIN(1); bf16_t* pb_ = P_PB;
;         for (size_t i = (size_t)bx * 512 + K_TID; i < n8; i += (size_t)G * 512) {
;             const f32x4 v0 = *(const f32x4*)(pp_ + 8 * i), v1 = *(const f32x4*)(pp_ + 8 * i + 4);
;             u32x4 w; w.x = pk2(v0[0], v0[1]); w.y = pk2(v0[2], v0[3]); w.z = pk2(v1[0], v1[1]); w.w = pk2(v1[2], v1[3]);
;             *(u32x4*)(pb_ + 8 * i) = w;
;         }
.LBB0_164:
	s_or_b64 exec, exec, s[0:1]
	s_mov_b64 s[4:5], s[46:47]
	s_mov_b64 s[6:7], s[46:47]
	s_ashr_i32 s75, s74, 31
	v_mbcnt_lo_u32_b32 v2, s2, 0
	v_mbcnt_hi_u32_b32 v2, s2, v2
	s_lshl_b64 s[0:1], s[74:75], 9
	v_or_b32_e32 v6, s82, v2
	v_ashrrev_i32_e32 v7, 31, v6
	v_lshl_add_u64 v[2:3], s[0:1], 0, v[6:7]
	s_mov_b64 s[0:1], 0x200000
	v_cmp_gt_u64_e32 vcc, s[0:1], v[2:3]
	s_and_saveexec_b64 s[0:1], vcc
	s_cbranch_execz .LBB0_167
	s_load_dwordx2 s[2:3], s[4:5], 0x8
	s_load_dwordx2 s[8:9], s[6:7], 0x98
	s_load_dwordx2 s[10:11], s[46:47], 0xa0
	s_lshl_b64 s[6:7], s[74:75], 14
	v_lshlrev_b64 v[4:5], 5, v[6:7]
	s_mov_b64 s[12:13], 0x1fffff
	s_waitcnt lgkmcnt(0)
	s_ashr_i32 s11, s10, 31
	s_lshl_b64 s[4:5], s[10:11], 9
	s_add_u32 s2, s2, s6
	s_addc_u32 s3, s3, s7
	v_lshl_add_u64 v[4:5], s[2:3], 0, v[4:5]
	s_lshl_b64 s[6:7], s[10:11], 14
	s_lshl_b64 s[2:3], s[74:75], 13
	s_add_u32 s2, s8, s2
	s_addc_u32 s3, s9, s3
	v_lshl_add_u64 v[6:7], v[6:7], 4, s[2:3]
	s_mov_b64 s[2:3], 0x3804000
	v_lshl_add_u64 v[4:5], v[4:5], 0, 16
	v_lshl_add_u64 v[6:7], v[6:7], 0, s[2:3]
	s_lshl_b64 s[8:9], s[10:11], 13
	s_mov_b64 s[10:11], 0
	s_lshl_b64 s[98:99], s[4:5], 1
	s_add_u32 s98, s98, s4
	s_addc_u32 s99, s99, s5
.Lp4_head:
	v_lshl_add_u64 v[40:41], v[2:3], 0, s[98:99]
	v_cmp_lt_u64_e32 vcc, s[12:13], v[40:41]
	s_and_b64 s[100:101], vcc, exec
	s_cbranch_scc1 .Lp4_exit
	global_load_dwordx4 v[8:11], v[4:5], off offset:-16
	global_load_dwordx4 v[12:15], v[4:5], off
	v_lshl_add_u64 v[4:5], v[4:5], 0, s[6:7]
	global_load_dwordx4 v[16:19], v[4:5], off offset:-16
	global_load_dwordx4 v[20:23], v[4:5], off
	v_lshl_add_u64 v[4:5], v[4:5], 0, s[6:7]
	global_load_dwordx4 v[24:27], v[4:5], off offset:-16
	global_load_dwordx4 v[28:31], v[4:5], off
	v_lshl_add_u64 v[4:5], v[4:5], 0, s[6:7]
	global_load_dwordx4 v[32:35], v[4:5], off offset:-16
	global_load_dwordx4 v[36:39], v[4:5], off
	v_lshl_add_u64 v[4:5], v[4:5], 0, s[6:7]
	v_lshl_add_u64 v[2:3], v[2:3], 0, s[4:5]
	v_lshl_add_u64 v[2:3], v[2:3], 0, s[4:5]
	v_lshl_add_u64 v[2:3], v[2:3], 0, s[4:5]
	v_lshl_add_u64 v[2:3], v[2:3], 0, s[4:5]
	s_waitcnt vmcnt(6)
	v_cvt_pk_bf16_f32 v8, v8, v9
	v_cvt_pk_bf16_f32 v9, v10, v11
	v_cvt_pk_bf16_f32 v10, v12, v13
	v_cvt_pk_bf16_f32 v11, v14, v15
	global_store_dwordx4 v[6:7], v[8:11], off
	v_lshl_add_u64 v[6:7], v[6:7], 0, s[8:9]
	s_waitcnt vmcnt(5)
	v_cvt_pk_bf16_f32 v16, v16, v17
	v_cvt_pk_bf16_f32 v17, v18, v19
	v_cvt_pk_bf16_f32 v18, v20, v21
	v_cvt_pk_bf16_f32 v19, v22, v23
	global_store_dwordx4 v[6:7], v[16:19], off
	v_lshl_add_u64 v[6:7], v[6:7], 0, s[8:9]
	s_waitcnt vmcnt(4)
	v_cvt_pk_bf16_f32 v24, v24, v25
	v_cvt_pk_bf16_f32 v25, v26, v27
	v_cvt_pk_bf16_f32 v26, v28, v29
	v_cvt_pk_bf16_f32 v27, v30, v31
	global_store_dwordx4 v[6:7], v[24:27], off
	v_lshl_add_u64 v[6:7], v[6:7], 0, s[8:9]
	s_waitcnt vmcnt(3)
	v_cvt_pk_bf16_f32 v32, v32, v33
	v_cvt_pk_bf16_f32 v33, v34, v35
	v_cvt_pk_bf16_f32 v34, v36, v37
	v_cvt_pk_bf16_f32 v35, v38, v39
	global_store_dwordx4 v[6:7], v[32:35], off
	v_lshl_add_u64 v[6:7], v[6:7], 0, s[8:9]
	s_branch .Lp4_head
.Lp4_exit:
	v_cmp_lt_u64_e32 vcc, s[12:13], v[2:3]
	s_or_b64 s[10:11], vcc, s[10:11]
	s_andn2_b64 exec, exec, s[10:11]
	s_cbranch_execz .LBB0_167
